# in1 GEMM epilogue: rope tiles use a specialised epilogue copy; the 8 distinct cos/sin row loads are issued once up front into dead fragment registers instead of 16 serial load-wait-rotate blocks
# speedup vs baseline: 1.0143x; 1.0135x over previous
.LBB0_1264:
	ds_read_b128 v[150:153], v162
	ds_read_b128 v[166:169], v162 offset:1024
	ds_read_b128 v[170:173], v162 offset:2048
	ds_read_b128 v[174:177], v162 offset:3072
	s_add_u32 s18, s56, 0xfffc0080
	s_addc_u32 s62, s57, -1
	s_cmp_eq_u32 s74, 12
	s_cselect_b32 s65, s7, s62
	s_cselect_b32 s64, s35, s18
	s_cselect_b32 s63, s47, s73
	s_cselect_b32 s62, s49, s70
	v_lshl_add_u64 v[154:155], s[56:57], 0, v[142:143]
	s_add_i32 m0, s17, 0xc000
	ds_read_b128 v[178:181], v163
	ds_read_b128 v[182:185], v163 offset:1024
	ds_read_b128 v[186:189], v163 offset:2048
	ds_read_b128 v[190:193], v163 offset:3072
	ds_read_b128 v[194:197], v163 offset:4096
	ds_read_b128 v[198:201], v163 offset:5120
	ds_read_b128 v[202:205], v163 offset:6144
	ds_read_b128 v[206:209], v163 offset:7168
	global_load_lds_dwordx4 v[154:155], off
	v_lshl_add_u64 v[154:155], s[56:57], 0, v[144:145]
	s_add_i32 m0, s17, 0xe000
	s_nop 0
	global_load_lds_dwordx4 v[154:155], off
	s_waitcnt lgkmcnt(8)
	s_barrier
	s_waitcnt lgkmcnt(0)
	s_setprio 1
	s_waitcnt lgkmcnt(0)
	v_mfma_f32_16x16x32_bf16 v[124:127], v[150:153], v[178:181], v[124:127]
	v_mfma_f32_16x16x32_bf16 v[120:123], v[170:173], v[178:181], v[120:123]
	v_mfma_f32_16x16x32_bf16 v[116:119], v[150:153], v[186:189], v[116:119]
	v_mfma_f32_16x16x32_bf16 v[112:115], v[170:173], v[186:189], v[112:115]
	v_mfma_f32_16x16x32_bf16 v[108:111], v[150:153], v[194:197], v[108:111]
	v_mfma_f32_16x16x32_bf16 v[104:107], v[170:173], v[194:197], v[104:107]
	v_mfma_f32_16x16x32_bf16 v[100:103], v[150:153], v[202:205], v[100:103]
	v_mfma_f32_16x16x32_bf16 v[96:99], v[170:173], v[202:205], v[96:99]
	v_mfma_f32_16x16x32_bf16 v[124:127], v[166:169], v[182:185], v[124:127]
	v_mfma_f32_16x16x32_bf16 v[120:123], v[174:177], v[182:185], v[120:123]
	v_mfma_f32_16x16x32_bf16 v[116:119], v[166:169], v[190:193], v[116:119]
	v_mfma_f32_16x16x32_bf16 v[112:115], v[174:177], v[190:193], v[112:115]
	v_mfma_f32_16x16x32_bf16 v[108:111], v[166:169], v[198:201], v[108:111]
	v_mfma_f32_16x16x32_bf16 v[104:107], v[174:177], v[198:201], v[104:107]
	v_mfma_f32_16x16x32_bf16 v[100:103], v[166:169], v[206:209], v[100:103]
	v_mfma_f32_16x16x32_bf16 v[96:99], v[174:177], v[206:209], v[96:99]
	s_setprio 0
	s_barrier
	s_add_i32 s18, s68, s3
	v_lshl_add_u64 v[154:155], s[62:63], 0, v[130:131]
	s_mov_b32 m0, s18
	ds_read_b128 v[210:213], v164
	ds_read_b128 v[214:217], v164 offset:1024
	ds_read_b128 v[218:221], v164 offset:2048
	ds_read_b128 v[226:229], v164 offset:3072
	global_load_lds_dwordx4 v[154:155], off
	v_lshl_add_u64 v[222:223], s[62:63], 0, v[134:135]
	s_add_i32 m0, s18, 0x2000
	s_nop 0
	global_load_lds_dwordx4 v[222:223], off
	s_barrier
	s_waitcnt lgkmcnt(0)
	s_setprio 1
	s_waitcnt lgkmcnt(0)
	v_mfma_f32_16x16x32_bf16 v[60:63], v[210:213], v[178:181], v[60:63]
	v_mfma_f32_16x16x32_bf16 v[56:59], v[218:221], v[178:181], v[56:59]
	v_mfma_f32_16x16x32_bf16 v[52:55], v[210:213], v[186:189], v[52:55]
	v_mfma_f32_16x16x32_bf16 v[48:51], v[218:221], v[186:189], v[48:51]
	v_mfma_f32_16x16x32_bf16 v[44:47], v[210:213], v[194:197], v[44:47]
	v_mfma_f32_16x16x32_bf16 v[40:43], v[218:221], v[194:197], v[40:43]
	v_mfma_f32_16x16x32_bf16 v[36:39], v[210:213], v[202:205], v[36:39]
	v_mfma_f32_16x16x32_bf16 v[32:35], v[218:221], v[202:205], v[32:35]
	v_mfma_f32_16x16x32_bf16 v[60:63], v[214:217], v[182:185], v[60:63]
	v_mfma_f32_16x16x32_bf16 v[56:59], v[226:229], v[182:185], v[56:59]
	v_mfma_f32_16x16x32_bf16 v[52:55], v[214:217], v[190:193], v[52:55]
	v_mfma_f32_16x16x32_bf16 v[48:51], v[226:229], v[190:193], v[48:51]
	v_mfma_f32_16x16x32_bf16 v[44:47], v[214:217], v[198:201], v[44:47]
	v_mfma_f32_16x16x32_bf16 v[40:43], v[226:229], v[198:201], v[40:43]
	v_mfma_f32_16x16x32_bf16 v[36:39], v[214:217], v[206:209], v[36:39]
	v_mfma_f32_16x16x32_bf16 v[32:35], v[226:229], v[206:209], v[32:35]
	s_setprio 0
	s_mov_b32 m0, s17
	v_lshl_add_u64 v[230:231], s[64:65], 0, v[128:129]
	s_barrier
	ds_read_b128 v[178:181], v163 offset:16384
	ds_read_b128 v[182:185], v163 offset:17408
	ds_read_b128 v[186:189], v163 offset:18432
	ds_read_b128 v[190:193], v163 offset:19456
	ds_read_b128 v[194:197], v163 offset:20480
	ds_read_b128 v[198:201], v163 offset:21504
	ds_read_b128 v[202:205], v163 offset:22528
	ds_read_b128 v[206:209], v163 offset:23552
	global_load_lds_dwordx4 v[230:231], off
	v_lshl_add_u64 v[232:233], s[64:65], 0, v[132:133]
	s_mov_b32 m0, s19
	s_nop 0
	global_load_lds_dwordx4 v[232:233], off
	s_barrier
	s_waitcnt lgkmcnt(0)
	s_setprio 1
	s_waitcnt lgkmcnt(0)
	v_mfma_f32_16x16x32_bf16 v[92:95], v[150:153], v[178:181], v[92:95]
	v_mfma_f32_16x16x32_bf16 v[88:91], v[170:173], v[178:181], v[88:91]
	v_mfma_f32_16x16x32_bf16 v[84:87], v[150:153], v[186:189], v[84:87]
	v_mfma_f32_16x16x32_bf16 v[80:83], v[170:173], v[186:189], v[80:83]
	v_mfma_f32_16x16x32_bf16 v[76:79], v[150:153], v[194:197], v[76:79]
	v_mfma_f32_16x16x32_bf16 v[72:75], v[170:173], v[194:197], v[72:75]
	v_mfma_f32_16x16x32_bf16 v[68:71], v[150:153], v[202:205], v[68:71]
	v_mfma_f32_16x16x32_bf16 v[64:67], v[170:173], v[202:205], v[64:67]
	v_mfma_f32_16x16x32_bf16 v[92:95], v[166:169], v[182:185], v[92:95]
	v_mfma_f32_16x16x32_bf16 v[88:91], v[174:177], v[182:185], v[88:91]
	v_mfma_f32_16x16x32_bf16 v[84:87], v[166:169], v[190:193], v[84:87]
	v_mfma_f32_16x16x32_bf16 v[80:83], v[174:177], v[190:193], v[80:83]
	v_mfma_f32_16x16x32_bf16 v[76:79], v[166:169], v[198:201], v[76:79]
	v_mfma_f32_16x16x32_bf16 v[72:75], v[174:177], v[198:201], v[72:75]
	v_mfma_f32_16x16x32_bf16 v[68:71], v[166:169], v[206:209], v[68:71]
	v_mfma_f32_16x16x32_bf16 v[64:67], v[174:177], v[206:209], v[64:67]
	s_setprio 0
	s_barrier
	s_add_u32 s76, s62, 0x40000
	s_addc_u32 s77, s63, 0
	s_add_i32 s18, s69, s3
	v_lshl_add_u64 v[150:151], s[76:77], 0, v[130:131]
	s_mov_b32 m0, s18
	s_nop 0
	global_load_lds_dwordx4 v[150:151], off
	v_lshl_add_u64 v[150:151], s[76:77], 0, v[134:135]
	s_add_i32 m0, s18, 0x2000
	s_nop 0
	global_load_lds_dwordx4 v[150:151], off
	s_waitcnt vmcnt(6)
	s_barrier
	s_setprio 1
	v_mfma_f32_16x16x32_bf16 v[28:31], v[210:213], v[178:181], v[28:31]
	v_mfma_f32_16x16x32_bf16 v[24:27], v[218:221], v[178:181], v[24:27]
	v_mfma_f32_16x16x32_bf16 v[20:23], v[210:213], v[186:189], v[20:23]
	v_mfma_f32_16x16x32_bf16 v[16:19], v[218:221], v[186:189], v[16:19]
	v_mfma_f32_16x16x32_bf16 v[12:15], v[210:213], v[194:197], v[12:15]
	v_mfma_f32_16x16x32_bf16 v[8:11], v[218:221], v[194:197], v[8:11]
	v_mfma_f32_16x16x32_bf16 v[4:7], v[210:213], v[202:205], v[4:7]
	v_mfma_f32_16x16x32_bf16 v[0:3], v[218:221], v[202:205], v[0:3]
	v_mfma_f32_16x16x32_bf16 v[28:31], v[214:217], v[182:185], v[28:31]
	v_mfma_f32_16x16x32_bf16 v[24:27], v[226:229], v[182:185], v[24:27]
	v_mfma_f32_16x16x32_bf16 v[20:23], v[214:217], v[190:193], v[20:23]
	v_mfma_f32_16x16x32_bf16 v[16:19], v[226:229], v[190:193], v[16:19]
	v_mfma_f32_16x16x32_bf16 v[12:15], v[214:217], v[198:201], v[12:15]
	v_mfma_f32_16x16x32_bf16 v[8:11], v[226:229], v[198:201], v[8:11]
	v_mfma_f32_16x16x32_bf16 v[4:7], v[214:217], v[206:209], v[4:7]
	v_mfma_f32_16x16x32_bf16 v[0:3], v[226:229], v[206:209], v[0:3]
	s_setprio 0
	s_add_i32 s18, 0, 0x18000
	v_add_u32_e32 v136, s18, v157
	s_barrier
	ds_read_b128 v[150:153], v136
	ds_read_b128 v[166:169], v136 offset:1024
	ds_read_b128 v[170:173], v136 offset:2048
	ds_read_b128 v[174:177], v136 offset:3072
	s_add_u32 s64, s64, 0x40000
	s_addc_u32 s65, s65, 0
	s_mov_b32 m0, s28
	v_lshl_add_u64 v[210:211], s[64:65], 0, v[128:129]
	ds_read_b128 v[178:181], v163 offset:32768
	ds_read_b128 v[182:185], v163 offset:33792
	ds_read_b128 v[186:189], v163 offset:34816
	ds_read_b128 v[190:193], v163 offset:35840
	ds_read_b128 v[194:197], v163 offset:36864
	ds_read_b128 v[198:201], v163 offset:37888
	ds_read_b128 v[202:205], v163 offset:38912
	ds_read_b128 v[206:209], v163 offset:39936
	global_load_lds_dwordx4 v[210:211], off
	v_lshl_add_u64 v[210:211], s[64:65], 0, v[132:133]
	s_mov_b32 m0, s29
	s_nop 0
	global_load_lds_dwordx4 v[210:211], off
	s_waitcnt lgkmcnt(8)
	s_barrier
	s_waitcnt lgkmcnt(0)
	s_setprio 1
	s_waitcnt lgkmcnt(0)
	v_mfma_f32_16x16x32_bf16 v[124:127], v[150:153], v[178:181], v[124:127]
	v_mfma_f32_16x16x32_bf16 v[120:123], v[170:173], v[178:181], v[120:123]
	v_mfma_f32_16x16x32_bf16 v[116:119], v[150:153], v[186:189], v[116:119]
	v_mfma_f32_16x16x32_bf16 v[112:115], v[170:173], v[186:189], v[112:115]
	v_mfma_f32_16x16x32_bf16 v[108:111], v[150:153], v[194:197], v[108:111]
	v_mfma_f32_16x16x32_bf16 v[104:107], v[170:173], v[194:197], v[104:107]
	v_mfma_f32_16x16x32_bf16 v[100:103], v[150:153], v[202:205], v[100:103]
	v_mfma_f32_16x16x32_bf16 v[96:99], v[170:173], v[202:205], v[96:99]
	v_mfma_f32_16x16x32_bf16 v[124:127], v[166:169], v[182:185], v[124:127]
	v_mfma_f32_16x16x32_bf16 v[120:123], v[174:177], v[182:185], v[120:123]
	v_mfma_f32_16x16x32_bf16 v[116:119], v[166:169], v[190:193], v[116:119]
	v_mfma_f32_16x16x32_bf16 v[112:115], v[174:177], v[190:193], v[112:115]
	v_mfma_f32_16x16x32_bf16 v[108:111], v[166:169], v[198:201], v[108:111]
	v_mfma_f32_16x16x32_bf16 v[104:107], v[174:177], v[198:201], v[104:107]
	v_mfma_f32_16x16x32_bf16 v[100:103], v[166:169], v[206:209], v[100:103]
	v_mfma_f32_16x16x32_bf16 v[96:99], v[174:177], v[206:209], v[96:99]
	s_setprio 0
	s_barrier
	s_add_i32 s64, 0, 0x1c000
	s_add_i32 s18, s18, s3
	v_add_u32_e32 v136, s64, v157
	v_lshl_add_u64 v[154:155], v[154:155], 0, s[36:37]
	s_mov_b32 m0, s18
	ds_read_b128 v[210:213], v136
	ds_read_b128 v[214:217], v136 offset:1024
	ds_read_b128 v[218:221], v136 offset:2048
	ds_read_b128 v[226:229], v136 offset:3072
	global_load_lds_dwordx4 v[154:155], off
	v_lshl_add_u64 v[154:155], v[222:223], 0, s[36:37]
	s_add_i32 m0, s18, 0x2000
	s_nop 0
	global_load_lds_dwordx4 v[154:155], off
	s_barrier
	s_waitcnt lgkmcnt(0)
	s_setprio 1
	s_waitcnt lgkmcnt(0)
	v_mfma_f32_16x16x32_bf16 v[60:63], v[210:213], v[178:181], v[60:63]
	v_mfma_f32_16x16x32_bf16 v[56:59], v[218:221], v[178:181], v[56:59]
	v_mfma_f32_16x16x32_bf16 v[52:55], v[210:213], v[186:189], v[52:55]
	v_mfma_f32_16x16x32_bf16 v[48:51], v[218:221], v[186:189], v[48:51]
	v_mfma_f32_16x16x32_bf16 v[44:47], v[210:213], v[194:197], v[44:47]
	v_mfma_f32_16x16x32_bf16 v[40:43], v[218:221], v[194:197], v[40:43]
	v_mfma_f32_16x16x32_bf16 v[36:39], v[210:213], v[202:205], v[36:39]
	v_mfma_f32_16x16x32_bf16 v[32:35], v[218:221], v[202:205], v[32:35]
	v_mfma_f32_16x16x32_bf16 v[60:63], v[214:217], v[182:185], v[60:63]
	v_mfma_f32_16x16x32_bf16 v[56:59], v[226:229], v[182:185], v[56:59]
	v_mfma_f32_16x16x32_bf16 v[52:55], v[214:217], v[190:193], v[52:55]
	v_mfma_f32_16x16x32_bf16 v[48:51], v[226:229], v[190:193], v[48:51]
	v_mfma_f32_16x16x32_bf16 v[44:47], v[214:217], v[198:201], v[44:47]
	v_mfma_f32_16x16x32_bf16 v[40:43], v[226:229], v[198:201], v[40:43]
	v_mfma_f32_16x16x32_bf16 v[36:39], v[214:217], v[206:209], v[36:39]
	v_mfma_f32_16x16x32_bf16 v[32:35], v[226:229], v[206:209], v[32:35]
	s_setprio 0
	s_mov_b32 m0, s59
	v_lshl_add_u64 v[154:155], v[230:231], 0, s[36:37]
	s_barrier
	ds_read_b128 v[178:181], v163 offset:49152
	ds_read_b128 v[182:185], v163 offset:50176
	ds_read_b128 v[186:189], v163 offset:51200
	ds_read_b128 v[190:193], v163 offset:52224
	ds_read_b128 v[194:197], v163 offset:53248
	ds_read_b128 v[198:201], v163 offset:54272
	ds_read_b128 v[202:205], v163 offset:55296
	ds_read_b128 v[206:209], v163 offset:56320
	global_load_lds_dwordx4 v[154:155], off
	v_lshl_add_u64 v[154:155], v[232:233], 0, s[36:37]
	s_mov_b32 m0, s66
	s_nop 0
	global_load_lds_dwordx4 v[154:155], off
	s_barrier
	s_waitcnt lgkmcnt(0)
	s_setprio 1
	s_waitcnt lgkmcnt(0)
	v_mfma_f32_16x16x32_bf16 v[92:95], v[150:153], v[178:181], v[92:95]
	v_mfma_f32_16x16x32_bf16 v[88:91], v[170:173], v[178:181], v[88:91]
	v_mfma_f32_16x16x32_bf16 v[84:87], v[150:153], v[186:189], v[84:87]
	v_mfma_f32_16x16x32_bf16 v[80:83], v[170:173], v[186:189], v[80:83]
	v_mfma_f32_16x16x32_bf16 v[76:79], v[150:153], v[194:197], v[76:79]
	v_mfma_f32_16x16x32_bf16 v[72:75], v[170:173], v[194:197], v[72:75]
	v_mfma_f32_16x16x32_bf16 v[68:71], v[150:153], v[202:205], v[68:71]
	v_mfma_f32_16x16x32_bf16 v[64:67], v[170:173], v[202:205], v[64:67]
	v_mfma_f32_16x16x32_bf16 v[92:95], v[166:169], v[182:185], v[92:95]
	v_mfma_f32_16x16x32_bf16 v[88:91], v[174:177], v[182:185], v[88:91]
	v_mfma_f32_16x16x32_bf16 v[84:87], v[166:169], v[190:193], v[84:87]
	v_mfma_f32_16x16x32_bf16 v[80:83], v[174:177], v[190:193], v[80:83]
	v_mfma_f32_16x16x32_bf16 v[76:79], v[166:169], v[198:201], v[76:79]
	v_mfma_f32_16x16x32_bf16 v[72:75], v[174:177], v[198:201], v[72:75]
	v_mfma_f32_16x16x32_bf16 v[68:71], v[166:169], v[206:209], v[68:71]
	v_mfma_f32_16x16x32_bf16 v[64:67], v[174:177], v[206:209], v[64:67]
	s_setprio 0
	s_barrier
	s_add_u32 s62, s62, 0x40080
	s_addc_u32 s63, s63, 0
	s_add_i32 s18, s64, s3
	v_lshl_add_u64 v[150:151], s[62:63], 0, v[130:131]
	s_mov_b32 m0, s18
	s_nop 0
	global_load_lds_dwordx4 v[150:151], off
	v_lshl_add_u64 v[150:151], s[62:63], 0, v[134:135]
	s_add_i32 m0, s18, 0x2000
	s_nop 0
	global_load_lds_dwordx4 v[150:151], off
	s_waitcnt vmcnt(6)
	s_barrier
	s_setprio 1
	v_mfma_f32_16x16x32_bf16 v[28:31], v[210:213], v[178:181], v[28:31]
	v_mfma_f32_16x16x32_bf16 v[24:27], v[218:221], v[178:181], v[24:27]
	v_mfma_f32_16x16x32_bf16 v[20:23], v[210:213], v[186:189], v[20:23]
	v_mfma_f32_16x16x32_bf16 v[16:19], v[218:221], v[186:189], v[16:19]
	v_mfma_f32_16x16x32_bf16 v[12:15], v[210:213], v[194:197], v[12:15]
	v_mfma_f32_16x16x32_bf16 v[8:11], v[218:221], v[194:197], v[8:11]
	v_mfma_f32_16x16x32_bf16 v[4:7], v[210:213], v[202:205], v[4:7]
	v_mfma_f32_16x16x32_bf16 v[0:3], v[218:221], v[202:205], v[0:3]
	v_mfma_f32_16x16x32_bf16 v[28:31], v[214:217], v[182:185], v[28:31]
	v_mfma_f32_16x16x32_bf16 v[24:27], v[226:229], v[182:185], v[24:27]
	v_mfma_f32_16x16x32_bf16 v[20:23], v[214:217], v[190:193], v[20:23]
	v_mfma_f32_16x16x32_bf16 v[16:19], v[226:229], v[190:193], v[16:19]
	v_mfma_f32_16x16x32_bf16 v[12:15], v[214:217], v[198:201], v[12:15]
	v_mfma_f32_16x16x32_bf16 v[8:11], v[226:229], v[198:201], v[8:11]
	v_mfma_f32_16x16x32_bf16 v[4:7], v[214:217], v[206:209], v[4:7]
	v_mfma_f32_16x16x32_bf16 v[0:3], v[226:229], v[206:209], v[0:3]
	s_setprio 0
	s_add_i32 s74, s74, 2
	s_add_u32 s56, s56, 0x100
	s_addc_u32 s57, s57, 0
	s_add_u32 s70, s70, 0x100
	s_addc_u32 s73, s73, 0
	s_cmp_gt_u32 s74, 13
	s_barrier
	s_cbranch_scc0 .LBB0_1264
	s_lshl_b32 s47, s6, 8
	s_add_i32 s47, s47, s58
	s_cmp_lt_i32 s54, 8
	s_cselect_b64 s[56:57], -1, 0
	s_cmp_gt_i32 s6, 31
	s_cselect_b64 s[6:7], -1, 0
	s_and_b64 s[56:57], s[56:57], s[6:7]
	v_cndmask_b32_e64 v136, 0, 1, s[56:57]
	v_cmp_ne_u32_e64 s[6:7], 1, v136
	s_andn2_b64 vcc, exec, s[56:57]
	s_bfe_u32 s35, s47, 0x40006
	s_cbranch_vccnz .LBB0_1267
	s_branch .Lrope_epi
.LBB0_1267:
	s_and_b32 s18, s54, -4
	s_cmp_eq_u32 s18, 4
	s_cselect_b64 vcc, -1, 0
	v_or_b32_e32 v152, s47, v156
	v_cndmask_b32_e32 v150, 1.0, v165, vcc
	v_pk_mul_f32 v[124:125], v[150:151], v[124:125] op_sel_hi:[0,1]
	v_pk_mul_f32 v[120:121], v[150:151], v[120:121] op_sel_hi:[0,1]
	v_ashrrev_i32_e32 v153, 31, v152
	v_lshl_or_b32 v154, s54, 8, v158
	v_pk_mul_f32 v[166:167], v[150:151], v[122:123] op_sel_hi:[0,1]
	v_cvt_pk_bf16_f32 v122, v124, v125
	v_cvt_pk_bf16_f32 v124, v120, v121
	v_lshlrev_b64 v[120:121], 13, v[152:153]
	v_ashrrev_i32_e32 v155, 31, v154
	v_pk_mul_f32 v[126:127], v[150:151], v[126:127] op_sel_hi:[0,1]
	v_lshl_add_u64 v[120:121], s[60:61], 0, v[120:121]
	v_cvt_pk_bf16_f32 v123, v126, v127
	v_cvt_pk_bf16_f32 v125, v166, v167
	v_lshl_add_u64 v[120:121], v[154:155], 1, v[120:121]
	s_and_b64 vcc, exec, s[6:7]
	global_store_dwordx4 v[120:121], v[122:125], off
	s_cbranch_vccnz .LBB0_1269
.LBB0_1269:
	v_mov_b32_e32 v151, v150
	v_or_b32_e32 v122, 16, v152
	v_pk_mul_f32 v[116:117], v[150:151], v[116:117]
	v_pk_mul_f32 v[112:113], v[150:151], v[112:113]
	v_ashrrev_i32_e32 v123, 31, v122
	v_pk_mul_f32 v[124:125], v[150:151], v[114:115]
	v_cvt_pk_bf16_f32 v114, v116, v117
	v_cvt_pk_bf16_f32 v116, v112, v113
	v_lshlrev_b64 v[112:113], 13, v[122:123]
	v_pk_mul_f32 v[118:119], v[150:151], v[118:119]
	v_lshl_add_u64 v[112:113], s[60:61], 0, v[112:113]
	v_cvt_pk_bf16_f32 v115, v118, v119
	v_cvt_pk_bf16_f32 v117, v124, v125
	v_lshl_add_u64 v[112:113], v[154:155], 1, v[112:113]
	s_and_b64 vcc, exec, s[6:7]
	global_store_dwordx4 v[112:113], v[114:117], off
	s_cbranch_vccnz .LBB0_1271
.LBB0_1271:
	s_nop 0
	v_or_b32_e32 v114, 32, v152
	v_pk_mul_f32 v[108:109], v[150:151], v[108:109]
	v_pk_mul_f32 v[104:105], v[150:151], v[104:105]
	v_ashrrev_i32_e32 v115, 31, v114
	v_pk_mul_f32 v[116:117], v[150:151], v[106:107]
	v_cvt_pk_bf16_f32 v106, v108, v109
	v_cvt_pk_bf16_f32 v108, v104, v105
	v_lshlrev_b64 v[104:105], 13, v[114:115]
	v_pk_mul_f32 v[110:111], v[150:151], v[110:111]
	v_lshl_add_u64 v[104:105], s[60:61], 0, v[104:105]
	v_cvt_pk_bf16_f32 v107, v110, v111
	v_cvt_pk_bf16_f32 v109, v116, v117
	v_lshl_add_u64 v[104:105], v[154:155], 1, v[104:105]
	s_and_b64 vcc, exec, s[6:7]
	global_store_dwordx4 v[104:105], v[106:109], off
	s_cbranch_vccnz .LBB0_1273
.LBB0_1273:
	s_nop 0
	v_or_b32_e32 v106, 48, v152
	v_pk_mul_f32 v[100:101], v[150:151], v[100:101]
	v_pk_mul_f32 v[96:97], v[150:151], v[96:97]
	v_ashrrev_i32_e32 v107, 31, v106
	v_pk_mul_f32 v[108:109], v[150:151], v[98:99]
	v_cvt_pk_bf16_f32 v98, v100, v101
	v_cvt_pk_bf16_f32 v100, v96, v97
	v_lshlrev_b64 v[96:97], 13, v[106:107]
	v_pk_mul_f32 v[102:103], v[150:151], v[102:103]
	v_lshl_add_u64 v[96:97], s[60:61], 0, v[96:97]
	v_cvt_pk_bf16_f32 v99, v102, v103
	v_cvt_pk_bf16_f32 v101, v108, v109
	v_lshl_add_u64 v[96:97], v[154:155], 1, v[96:97]
	global_store_dwordx4 v[96:97], v[98:101], off
	s_and_b64 vcc, exec, s[6:7]
	s_nop 0
	v_add_u32_e32 v98, 0x80, v152
	v_bfe_u32 v100, v98, 6, 4
	v_cndmask_b32_e64 v99, v156, v100, s[0:1]
	v_lshlrev_b32_e32 v136, 7, v99
	s_cbranch_vccnz .LBB0_1275
.LBB0_1275:
	v_pk_mul_f32 v[92:93], v[150:151], v[92:93]
	v_pk_mul_f32 v[94:95], v[150:151], v[94:95]
	v_pk_mul_f32 v[88:89], v[150:151], v[88:89]
	v_ashrrev_i32_e32 v99, 31, v98
	v_cvt_pk_bf16_f32 v92, v92, v93
	v_cvt_pk_bf16_f32 v93, v94, v95
	v_cvt_pk_bf16_f32 v94, v88, v89
	v_lshlrev_b64 v[88:89], 13, v[98:99]
	v_pk_mul_f32 v[90:91], v[150:151], v[90:91]
	v_lshl_add_u64 v[88:89], s[60:61], 0, v[88:89]
	v_cvt_pk_bf16_f32 v95, v90, v91
	v_lshl_add_u64 v[90:91], v[154:155], 1, v[88:89]
	v_cndmask_b32_e64 v88, v159, v100, s[0:1]
	s_and_b64 vcc, exec, s[6:7]
	v_lshlrev_b32_e32 v88, 7, v88
	global_store_dwordx4 v[90:91], v[92:95], off
	s_cbranch_vccnz .LBB0_1277
.LBB0_1277:
	v_pk_mul_f32 v[84:85], v[150:151], v[84:85]
	v_pk_mul_f32 v[80:81], v[150:151], v[80:81]
	v_pk_mul_f32 v[92:93], v[150:151], v[82:83]
	v_cvt_pk_bf16_f32 v82, v84, v85
	v_cvt_pk_bf16_f32 v84, v80, v81
	v_lshlrev_b64 v[80:81], 13, v[152:153]
	v_lshl_add_u64 v[80:81], s[60:61], 0, v[80:81]
	v_pk_mul_f32 v[86:87], v[150:151], v[86:87]
	v_lshl_add_u64 v[80:81], v[154:155], 1, v[80:81]
	v_cvt_pk_bf16_f32 v83, v86, v87
	v_add_co_u32_e32 v86, vcc, 0x120000, v80
	v_cvt_pk_bf16_f32 v85, v92, v93
	s_nop 0
	v_addc_co_u32_e32 v87, vcc, 0, v81, vcc
	global_store_dwordx4 v[86:87], v[82:85], off
	s_and_b64 vcc, exec, s[6:7]
	s_nop 0
	v_cndmask_b32_e64 v82, v160, v100, s[0:1]
	v_lshlrev_b32_e32 v82, 7, v82
	s_cbranch_vccnz .LBB0_1279
.LBB0_1279:
	v_pk_mul_f32 v[76:77], v[150:151], v[76:77]
	v_pk_mul_f32 v[78:79], v[150:151], v[78:79]
	v_pk_mul_f32 v[84:85], v[150:151], v[72:73]
	v_pk_mul_f32 v[86:87], v[150:151], v[74:75]
	v_cvt_pk_bf16_f32 v72, v76, v77
	v_add_co_u32_e32 v76, vcc, 0x140000, v80
	v_cvt_pk_bf16_f32 v73, v78, v79
	v_cvt_pk_bf16_f32 v74, v84, v85
	v_cvt_pk_bf16_f32 v75, v86, v87
	v_addc_co_u32_e32 v77, vcc, 0, v81, vcc
	global_store_dwordx4 v[76:77], v[72:75], off
	s_and_b64 vcc, exec, s[6:7]
	s_nop 0
	v_cndmask_b32_e64 v72, v161, v100, s[0:1]
	v_lshlrev_b32_e32 v72, 7, v72
	s_cbranch_vccnz .LBB0_1281
.LBB0_1281:
	v_pk_mul_f32 v[68:69], v[150:151], v[68:69]
	v_pk_mul_f32 v[64:65], v[150:151], v[64:65]
	v_pk_mul_f32 v[74:75], v[150:151], v[66:67]
	v_cvt_pk_bf16_f32 v66, v68, v69
	v_cvt_pk_bf16_f32 v68, v64, v65
	v_lshlrev_b64 v[64:65], 13, v[152:153]
	v_lshl_add_u64 v[64:65], s[60:61], 0, v[64:65]
	v_pk_mul_f32 v[70:71], v[150:151], v[70:71]
	v_lshl_add_u64 v[64:65], v[154:155], 1, v[64:65]
	v_cvt_pk_bf16_f32 v67, v70, v71
	v_add_co_u32_e32 v70, vcc, 0x160000, v64
	v_cvt_pk_bf16_f32 v69, v74, v75
	s_nop 0
	v_addc_co_u32_e32 v71, vcc, 0, v65, vcc
	s_and_b64 vcc, exec, s[6:7]
	global_store_dwordx4 v[70:71], v[66:69], off
	s_cbranch_vccnz .LBB0_1283
.LBB0_1283:
	v_pk_mul_f32 v[60:61], v[150:151], v[60:61]
	v_pk_mul_f32 v[62:63], v[150:151], v[62:63]
	v_pk_mul_f32 v[66:67], v[150:151], v[56:57]
	v_pk_mul_f32 v[68:69], v[150:151], v[58:59]
	v_cvt_pk_bf16_f32 v56, v60, v61
	v_cvt_pk_bf16_f32 v57, v62, v63
	v_cvt_pk_bf16_f32 v58, v66, v67
	v_cvt_pk_bf16_f32 v59, v68, v69
	s_and_b64 vcc, exec, s[6:7]
	global_store_dwordx4 v[120:121], v[56:59], off offset:256
	s_cbranch_vccnz .LBB0_1285
.LBB0_1285:
	v_pk_mul_f32 v[52:53], v[150:151], v[52:53]
	v_pk_mul_f32 v[54:55], v[150:151], v[54:55]
	v_pk_mul_f32 v[56:57], v[150:151], v[48:49]
	v_pk_mul_f32 v[58:59], v[150:151], v[50:51]
	v_cvt_pk_bf16_f32 v48, v52, v53
	v_cvt_pk_bf16_f32 v49, v54, v55
	v_cvt_pk_bf16_f32 v50, v56, v57
	v_cvt_pk_bf16_f32 v51, v58, v59
	s_and_b64 vcc, exec, s[6:7]
	global_store_dwordx4 v[112:113], v[48:51], off offset:256
	s_cbranch_vccnz .LBB0_1287
.LBB0_1287:
	v_pk_mul_f32 v[44:45], v[150:151], v[44:45]
	v_pk_mul_f32 v[46:47], v[150:151], v[46:47]
	v_pk_mul_f32 v[48:49], v[150:151], v[40:41]
	v_pk_mul_f32 v[50:51], v[150:151], v[42:43]
	v_cvt_pk_bf16_f32 v40, v44, v45
	v_cvt_pk_bf16_f32 v41, v46, v47
	v_cvt_pk_bf16_f32 v42, v48, v49
	v_cvt_pk_bf16_f32 v43, v50, v51
	s_and_b64 vcc, exec, s[6:7]
	global_store_dwordx4 v[104:105], v[40:43], off offset:256
	s_cbranch_vccnz .LBB0_1289
.LBB0_1289:
	v_pk_mul_f32 v[36:37], v[150:151], v[36:37]
	v_pk_mul_f32 v[38:39], v[150:151], v[38:39]
	v_pk_mul_f32 v[40:41], v[150:151], v[32:33]
	v_pk_mul_f32 v[42:43], v[150:151], v[34:35]
	v_cvt_pk_bf16_f32 v32, v36, v37
	v_cvt_pk_bf16_f32 v33, v38, v39
	v_cvt_pk_bf16_f32 v34, v40, v41
	v_cvt_pk_bf16_f32 v35, v42, v43
	s_and_b64 vcc, exec, s[6:7]
	global_store_dwordx4 v[96:97], v[32:35], off offset:256
	s_cbranch_vccnz .LBB0_1291
.LBB0_1291:
	v_pk_mul_f32 v[28:29], v[150:151], v[28:29]
	v_pk_mul_f32 v[30:31], v[150:151], v[30:31]
	v_pk_mul_f32 v[32:33], v[150:151], v[24:25]
	v_pk_mul_f32 v[34:35], v[150:151], v[26:27]
	v_cvt_pk_bf16_f32 v24, v28, v29
	v_cvt_pk_bf16_f32 v25, v30, v31
	v_cvt_pk_bf16_f32 v26, v32, v33
	v_cvt_pk_bf16_f32 v27, v34, v35
	s_and_b64 vcc, exec, s[6:7]
	global_store_dwordx4 v[90:91], v[24:27], off offset:256
	s_cbranch_vccnz .LBB0_1293
.LBB0_1293:
	v_pk_mul_f32 v[20:21], v[150:151], v[20:21]
	v_pk_mul_f32 v[22:23], v[150:151], v[22:23]
	v_pk_mul_f32 v[26:27], v[150:151], v[16:17]
	v_pk_mul_f32 v[28:29], v[150:151], v[18:19]
	v_lshl_add_u64 v[24:25], v[80:81], 0, s[38:39]
	v_cvt_pk_bf16_f32 v16, v20, v21
	v_cvt_pk_bf16_f32 v17, v22, v23
	v_cvt_pk_bf16_f32 v18, v26, v27
	v_cvt_pk_bf16_f32 v19, v28, v29
	s_and_b64 vcc, exec, s[6:7]
	global_store_dwordx4 v[24:25], v[16:19], off offset:256
	s_cbranch_vccnz .LBB0_1295
.LBB0_1295:
	v_pk_mul_f32 v[12:13], v[150:151], v[12:13]
	v_pk_mul_f32 v[14:15], v[150:151], v[14:15]
	v_pk_mul_f32 v[18:19], v[150:151], v[8:9]
	v_pk_mul_f32 v[20:21], v[150:151], v[10:11]
	v_lshl_add_u64 v[16:17], v[80:81], 0, s[40:41]
	v_cvt_pk_bf16_f32 v8, v12, v13
	v_cvt_pk_bf16_f32 v9, v14, v15
	v_cvt_pk_bf16_f32 v10, v18, v19
	v_cvt_pk_bf16_f32 v11, v20, v21
	s_and_b64 vcc, exec, s[6:7]
	global_store_dwordx4 v[16:17], v[8:11], off offset:256
	s_cbranch_vccnz .LBB0_1260
	s_branch .LBB0_1260
.Lrope_epi:
	v_or_b32_e32 v250, s47, v156
	v_add_u32_e32 v250, 0x80, v250
	v_bfe_u32 v250, v250, 6, 4
	v_mov_b32_e32 v251, s35
	v_cndmask_b32_e64 v180, v156, v251, s[0:1]
	v_lshlrev_b32_e32 v180, 7, v180
	v_mov_b32_e32 v181, 0
	v_lshl_add_u64 v[182:183], v[140:141], 0, v[180:181]
	v_lshl_add_u64 v[178:179], v[138:139], 0, v[180:181]
	global_load_dwordx4 v[178:181], v[178:179], off
	global_load_dwordx4 v[182:185], v[182:183], off
	v_cndmask_b32_e64 v188, v159, v251, s[0:1]
	v_lshlrev_b32_e32 v188, 7, v188
	v_mov_b32_e32 v189, 0
	v_lshl_add_u64 v[190:191], v[140:141], 0, v[188:189]
	v_lshl_add_u64 v[186:187], v[138:139], 0, v[188:189]
	global_load_dwordx4 v[186:189], v[186:187], off
	global_load_dwordx4 v[190:193], v[190:191], off
	v_cndmask_b32_e64 v196, v160, v251, s[0:1]
	v_lshlrev_b32_e32 v196, 7, v196
	v_mov_b32_e32 v197, 0
	v_lshl_add_u64 v[198:199], v[140:141], 0, v[196:197]
	v_lshl_add_u64 v[194:195], v[138:139], 0, v[196:197]
	global_load_dwordx4 v[194:197], v[194:195], off
	global_load_dwordx4 v[198:201], v[198:199], off
	v_cndmask_b32_e64 v204, v161, v251, s[0:1]
	v_lshlrev_b32_e32 v204, 7, v204
	v_mov_b32_e32 v205, 0
	v_lshl_add_u64 v[206:207], v[140:141], 0, v[204:205]
	v_lshl_add_u64 v[202:203], v[138:139], 0, v[204:205]
	global_load_dwordx4 v[202:205], v[202:203], off
	global_load_dwordx4 v[206:209], v[206:207], off
	v_cndmask_b32_e64 v212, v156, v250, s[0:1]
	v_lshlrev_b32_e32 v212, 7, v212
	v_mov_b32_e32 v213, 0
	v_lshl_add_u64 v[214:215], v[140:141], 0, v[212:213]
	v_lshl_add_u64 v[210:211], v[138:139], 0, v[212:213]
	global_load_dwordx4 v[210:213], v[210:211], off
	global_load_dwordx4 v[214:217], v[214:215], off
	v_cndmask_b32_e64 v220, v159, v250, s[0:1]
	v_lshlrev_b32_e32 v220, 7, v220
	v_mov_b32_e32 v221, 0
	v_lshl_add_u64 v[226:227], v[140:141], 0, v[220:221]
	v_lshl_add_u64 v[218:219], v[138:139], 0, v[220:221]
	global_load_dwordx4 v[218:221], v[218:219], off
	global_load_dwordx4 v[226:229], v[226:227], off
	v_cndmask_b32_e64 v236, v160, v250, s[0:1]
	v_lshlrev_b32_e32 v236, 7, v236
	v_mov_b32_e32 v237, 0
	v_lshl_add_u64 v[238:239], v[140:141], 0, v[236:237]
	v_lshl_add_u64 v[234:235], v[138:139], 0, v[236:237]
	global_load_dwordx4 v[234:237], v[234:235], off
	global_load_dwordx4 v[238:241], v[238:239], off
	v_cndmask_b32_e64 v244, v161, v250, s[0:1]
	v_lshlrev_b32_e32 v244, 7, v244
	v_mov_b32_e32 v245, 0
	v_lshl_add_u64 v[246:247], v[140:141], 0, v[244:245]
	v_lshl_add_u64 v[242:243], v[138:139], 0, v[244:245]
	global_load_dwordx4 v[242:245], v[242:243], off
	global_load_dwordx4 v[246:249], v[246:247], off
	s_nop 1
	s_waitcnt vmcnt(14)
	v_mov_b64_e32 v[150:151], v[178:179]
	v_mov_b64_e32 v[152:153], v[180:181]
	v_mov_b64_e32 v[166:167], v[182:183]
	v_mov_b64_e32 v[168:169], v[184:185]
	v_pk_mul_f32 v[154:155], v[124:125], v[150:151]
	v_pk_mul_f32 v[170:171], v[124:125], v[166:167] op_sel:[1,0] op_sel_hi:[0,0]
	v_pk_mul_f32 v[166:167], v[126:127], v[166:167] op_sel:[1,1] op_sel_hi:[0,1]
	v_pk_mul_f32 v[172:173], v[120:121], v[168:169] op_sel:[1,0] op_sel_hi:[0,0]
	v_mov_b32_e32 v168, v153
	v_mul_f32_e32 v136, v123, v169
	v_mul_f32_e32 v174, v123, v153
	v_pk_fma_f32 v[124:125], v[124:125], v[150:151], v[170:171] op_sel_hi:[1,0,1]
	v_pk_fma_f32 v[176:177], v[126:127], v[150:151], v[166:167] op_sel:[0,1,0] neg_lo:[0,0,1] neg_hi:[0,0,1]
	v_pk_fma_f32 v[126:127], v[126:127], v[150:151], v[166:167] op_sel:[0,1,0]
	v_pk_fma_f32 v[150:151], v[120:121], v[152:153], v[172:173] op_sel_hi:[1,0,1] neg_lo:[0,0,1] neg_hi:[0,0,1]
	v_pk_fma_f32 v[120:121], v[120:121], v[152:153], v[172:173] op_sel_hi:[1,0,1]
	v_mov_b32_e32 v152, v169
	v_pk_fma_f32 v[166:167], v[122:123], v[168:169], v[136:137] op_sel_hi:[1,1,0] neg_lo:[0,0,1] neg_hi:[0,0,1]
	v_pk_fma_f32 v[152:153], v[122:123], v[152:153], v[174:175] op_sel_hi:[1,1,0]
	v_sub_f32_e32 v124, v154, v170
	v_mov_b32_e32 v126, v176
	v_mov_b32_e32 v120, v150
	v_mov_b32_e32 v122, v166
	v_mov_b32_e32 v123, v152
.Lrope_1267:
	s_and_b32 s18, s54, -4
	s_cmp_eq_u32 s18, 4
	s_cselect_b64 vcc, -1, 0
	v_or_b32_e32 v152, s47, v156
	v_cndmask_b32_e32 v150, 1.0, v165, vcc
	v_pk_mul_f32 v[124:125], v[150:151], v[124:125] op_sel_hi:[0,1]
	v_pk_mul_f32 v[120:121], v[150:151], v[120:121] op_sel_hi:[0,1]
	v_ashrrev_i32_e32 v153, 31, v152
	v_lshl_or_b32 v154, s54, 8, v158
	v_pk_mul_f32 v[166:167], v[150:151], v[122:123] op_sel_hi:[0,1]
	v_cvt_pk_bf16_f32 v122, v124, v125
	v_cvt_pk_bf16_f32 v124, v120, v121
	v_lshlrev_b64 v[120:121], 13, v[152:153]
	v_ashrrev_i32_e32 v155, 31, v154
	v_pk_mul_f32 v[126:127], v[150:151], v[126:127] op_sel_hi:[0,1]
	v_lshl_add_u64 v[120:121], s[60:61], 0, v[120:121]
	v_cvt_pk_bf16_f32 v123, v126, v127
	v_cvt_pk_bf16_f32 v125, v166, v167
	v_lshl_add_u64 v[120:121], v[154:155], 1, v[120:121]
	s_and_b64 vcc, exec, s[6:7]
	global_store_dwordx4 v[120:121], v[122:125], off
	s_nop 1
	s_waitcnt vmcnt(13)
	v_mov_b64_e32 v[122:123], v[186:187]
	v_mov_b64_e32 v[124:125], v[188:189]
	v_mov_b64_e32 v[166:167], v[190:191]
	v_mov_b64_e32 v[168:169], v[192:193]
	v_pk_mul_f32 v[126:127], v[116:117], v[122:123]
	v_pk_mul_f32 v[170:171], v[116:117], v[166:167] op_sel:[1,0] op_sel_hi:[0,0]
	v_pk_mul_f32 v[166:167], v[118:119], v[166:167] op_sel:[1,1] op_sel_hi:[0,1]
	v_pk_mul_f32 v[172:173], v[112:113], v[168:169] op_sel:[1,0] op_sel_hi:[0,0]
	v_mov_b32_e32 v168, v125
	v_mul_f32_e32 v136, v115, v169
	v_mul_f32_e32 v174, v115, v125
	v_pk_fma_f32 v[116:117], v[116:117], v[122:123], v[170:171] op_sel_hi:[1,0,1]
	v_pk_fma_f32 v[176:177], v[118:119], v[122:123], v[166:167] op_sel:[0,1,0] neg_lo:[0,0,1] neg_hi:[0,0,1]
	v_pk_fma_f32 v[118:119], v[118:119], v[122:123], v[166:167] op_sel:[0,1,0]
	v_pk_fma_f32 v[122:123], v[112:113], v[124:125], v[172:173] op_sel_hi:[1,0,1] neg_lo:[0,0,1] neg_hi:[0,0,1]
	v_pk_fma_f32 v[112:113], v[112:113], v[124:125], v[172:173] op_sel_hi:[1,0,1]
	v_mov_b32_e32 v124, v169
	v_pk_fma_f32 v[166:167], v[114:115], v[168:169], v[136:137] op_sel_hi:[1,1,0] neg_lo:[0,0,1] neg_hi:[0,0,1]
	v_pk_fma_f32 v[124:125], v[114:115], v[124:125], v[174:175] op_sel_hi:[1,1,0]
	v_sub_f32_e32 v116, v126, v170
	v_mov_b32_e32 v118, v176
	v_mov_b32_e32 v112, v122
	v_mov_b32_e32 v114, v166
	v_mov_b32_e32 v115, v124
.Lrope_1269:
	v_mov_b32_e32 v151, v150
	v_or_b32_e32 v122, 16, v152
	v_pk_mul_f32 v[116:117], v[150:151], v[116:117]
	v_pk_mul_f32 v[112:113], v[150:151], v[112:113]
	v_ashrrev_i32_e32 v123, 31, v122
	v_pk_mul_f32 v[124:125], v[150:151], v[114:115]
	v_cvt_pk_bf16_f32 v114, v116, v117
	v_cvt_pk_bf16_f32 v116, v112, v113
	v_lshlrev_b64 v[112:113], 13, v[122:123]
	v_pk_mul_f32 v[118:119], v[150:151], v[118:119]
	v_lshl_add_u64 v[112:113], s[60:61], 0, v[112:113]
	v_cvt_pk_bf16_f32 v115, v118, v119
	v_cvt_pk_bf16_f32 v117, v124, v125
	v_lshl_add_u64 v[112:113], v[154:155], 1, v[112:113]
	s_and_b64 vcc, exec, s[6:7]
	global_store_dwordx4 v[112:113], v[114:117], off
	s_nop 1
	s_waitcnt vmcnt(12)
	v_mov_b64_e32 v[114:115], v[194:195]
	v_mov_b64_e32 v[116:117], v[196:197]
	v_mov_b64_e32 v[122:123], v[198:199]
	v_mov_b64_e32 v[124:125], v[200:201]
	v_pk_mul_f32 v[118:119], v[108:109], v[114:115]
	v_pk_mul_f32 v[126:127], v[108:109], v[122:123] op_sel:[1,0] op_sel_hi:[0,0]
	v_pk_mul_f32 v[122:123], v[110:111], v[122:123] op_sel:[1,1] op_sel_hi:[0,1]
	v_pk_mul_f32 v[166:167], v[104:105], v[124:125] op_sel:[1,0] op_sel_hi:[0,0]
	v_mov_b32_e32 v124, v117
	v_mul_f32_e32 v136, v107, v125
	v_mul_f32_e32 v168, v107, v117
	v_pk_fma_f32 v[108:109], v[108:109], v[114:115], v[126:127] op_sel_hi:[1,0,1]
	v_pk_fma_f32 v[170:171], v[110:111], v[114:115], v[122:123] op_sel:[0,1,0] neg_lo:[0,0,1] neg_hi:[0,0,1]
	v_pk_fma_f32 v[110:111], v[110:111], v[114:115], v[122:123] op_sel:[0,1,0]
	v_pk_fma_f32 v[114:115], v[104:105], v[116:117], v[166:167] op_sel_hi:[1,0,1] neg_lo:[0,0,1] neg_hi:[0,0,1]
	v_pk_fma_f32 v[104:105], v[104:105], v[116:117], v[166:167] op_sel_hi:[1,0,1]
	v_mov_b32_e32 v116, v125
	v_pk_fma_f32 v[122:123], v[106:107], v[124:125], v[136:137] op_sel_hi:[1,1,0] neg_lo:[0,0,1] neg_hi:[0,0,1]
	v_pk_fma_f32 v[116:117], v[106:107], v[116:117], v[168:169] op_sel_hi:[1,1,0]
	v_sub_f32_e32 v108, v118, v126
	v_mov_b32_e32 v110, v170
	v_mov_b32_e32 v104, v114
	v_mov_b32_e32 v106, v122
	v_mov_b32_e32 v107, v116
.Lrope_1271:
	s_nop 0
	v_or_b32_e32 v114, 32, v152
	v_pk_mul_f32 v[108:109], v[150:151], v[108:109]
	v_pk_mul_f32 v[104:105], v[150:151], v[104:105]
	v_ashrrev_i32_e32 v115, 31, v114
	v_pk_mul_f32 v[116:117], v[150:151], v[106:107]
	v_cvt_pk_bf16_f32 v106, v108, v109
	v_cvt_pk_bf16_f32 v108, v104, v105
	v_lshlrev_b64 v[104:105], 13, v[114:115]
	v_pk_mul_f32 v[110:111], v[150:151], v[110:111]
	v_lshl_add_u64 v[104:105], s[60:61], 0, v[104:105]
	v_cvt_pk_bf16_f32 v107, v110, v111
	v_cvt_pk_bf16_f32 v109, v116, v117
	v_lshl_add_u64 v[104:105], v[154:155], 1, v[104:105]
	s_and_b64 vcc, exec, s[6:7]
	global_store_dwordx4 v[104:105], v[106:109], off
	s_nop 1
	s_waitcnt vmcnt(11)
	v_mov_b64_e32 v[106:107], v[202:203]
	v_mov_b64_e32 v[108:109], v[204:205]
	v_mov_b64_e32 v[114:115], v[206:207]
	v_mov_b64_e32 v[116:117], v[208:209]
	v_pk_mul_f32 v[110:111], v[100:101], v[106:107]
	v_pk_mul_f32 v[118:119], v[100:101], v[114:115] op_sel:[1,0] op_sel_hi:[0,0]
	v_pk_mul_f32 v[114:115], v[102:103], v[114:115] op_sel:[1,1] op_sel_hi:[0,1]
	v_pk_mul_f32 v[122:123], v[96:97], v[116:117] op_sel:[1,0] op_sel_hi:[0,0]
	v_mov_b32_e32 v116, v109
	v_mul_f32_e32 v124, v99, v117
	v_mul_f32_e32 v126, v99, v109
	v_pk_fma_f32 v[100:101], v[100:101], v[106:107], v[118:119] op_sel_hi:[1,0,1]
	v_pk_fma_f32 v[166:167], v[102:103], v[106:107], v[114:115] op_sel:[0,1,0] neg_lo:[0,0,1] neg_hi:[0,0,1]
	v_pk_fma_f32 v[102:103], v[102:103], v[106:107], v[114:115] op_sel:[0,1,0]
	v_pk_fma_f32 v[106:107], v[96:97], v[108:109], v[122:123] op_sel_hi:[1,0,1] neg_lo:[0,0,1] neg_hi:[0,0,1]
	v_pk_fma_f32 v[96:97], v[96:97], v[108:109], v[122:123] op_sel_hi:[1,0,1]
	v_mov_b32_e32 v108, v117
	v_pk_fma_f32 v[114:115], v[98:99], v[116:117], v[124:125] op_sel_hi:[1,1,0] neg_lo:[0,0,1] neg_hi:[0,0,1]
	v_pk_fma_f32 v[108:109], v[98:99], v[108:109], v[126:127] op_sel_hi:[1,1,0]
	v_sub_f32_e32 v100, v110, v118
	v_mov_b32_e32 v102, v166
	v_mov_b32_e32 v96, v106
	v_mov_b32_e32 v98, v114
	v_mov_b32_e32 v99, v108
.Lrope_1273:
	s_nop 0
	v_or_b32_e32 v106, 48, v152
	v_pk_mul_f32 v[100:101], v[150:151], v[100:101]
	v_pk_mul_f32 v[96:97], v[150:151], v[96:97]
	v_ashrrev_i32_e32 v107, 31, v106
	v_pk_mul_f32 v[108:109], v[150:151], v[98:99]
	v_cvt_pk_bf16_f32 v98, v100, v101
	v_cvt_pk_bf16_f32 v100, v96, v97
	v_lshlrev_b64 v[96:97], 13, v[106:107]
	v_pk_mul_f32 v[102:103], v[150:151], v[102:103]
	v_lshl_add_u64 v[96:97], s[60:61], 0, v[96:97]
	v_cvt_pk_bf16_f32 v99, v102, v103
	v_cvt_pk_bf16_f32 v101, v108, v109
	v_lshl_add_u64 v[96:97], v[154:155], 1, v[96:97]
	global_store_dwordx4 v[96:97], v[98:101], off
	s_and_b64 vcc, exec, s[6:7]
	s_nop 0
	v_add_u32_e32 v98, 0x80, v152
	v_bfe_u32 v100, v98, 6, 4
	v_cndmask_b32_e64 v99, v156, v100, s[0:1]
	v_lshlrev_b32_e32 v136, 7, v99
	s_nop 1
	s_waitcnt vmcnt(10)
	v_mov_b64_e32 v[106:107], v[210:211]
	v_mov_b64_e32 v[108:109], v[212:213]
	v_mov_b64_e32 v[114:115], v[214:215]
	v_mov_b64_e32 v[116:117], v[216:217]
	v_pk_mul_f32 v[102:103], v[92:93], v[106:107]
	v_pk_mul_f32 v[110:111], v[92:93], v[114:115] op_sel:[1,0] op_sel_hi:[0,0]
	v_pk_mul_f32 v[114:115], v[94:95], v[114:115] op_sel:[1,1] op_sel_hi:[0,1]
	v_pk_mul_f32 v[118:119], v[88:89], v[116:117] op_sel:[1,0] op_sel_hi:[0,0]
	v_mov_b32_e32 v116, v109
	v_mul_f32_e32 v122, v91, v117
	v_mul_f32_e32 v124, v91, v109
	v_pk_fma_f32 v[92:93], v[92:93], v[106:107], v[110:111] op_sel_hi:[1,0,1]
	v_pk_fma_f32 v[126:127], v[94:95], v[106:107], v[114:115] op_sel:[0,1,0] neg_lo:[0,0,1] neg_hi:[0,0,1]
	v_pk_fma_f32 v[94:95], v[94:95], v[106:107], v[114:115] op_sel:[0,1,0]
	v_pk_fma_f32 v[106:107], v[88:89], v[108:109], v[118:119] op_sel_hi:[1,0,1] neg_lo:[0,0,1] neg_hi:[0,0,1]
	v_pk_fma_f32 v[88:89], v[88:89], v[108:109], v[118:119] op_sel_hi:[1,0,1]
	v_mov_b32_e32 v108, v117
	v_pk_fma_f32 v[114:115], v[90:91], v[116:117], v[122:123] op_sel_hi:[1,1,0] neg_lo:[0,0,1] neg_hi:[0,0,1]
	v_pk_fma_f32 v[108:109], v[90:91], v[108:109], v[124:125] op_sel_hi:[1,1,0]
	v_sub_f32_e32 v92, v102, v110
	v_mov_b32_e32 v94, v126
	v_mov_b32_e32 v88, v106
	v_mov_b32_e32 v90, v114
	v_mov_b32_e32 v91, v108
.Lrope_1275:
	v_pk_mul_f32 v[92:93], v[150:151], v[92:93]
	v_pk_mul_f32 v[94:95], v[150:151], v[94:95]
	v_pk_mul_f32 v[88:89], v[150:151], v[88:89]
	v_ashrrev_i32_e32 v99, 31, v98
	v_cvt_pk_bf16_f32 v92, v92, v93
	v_cvt_pk_bf16_f32 v93, v94, v95
	v_cvt_pk_bf16_f32 v94, v88, v89
	v_lshlrev_b64 v[88:89], 13, v[98:99]
	v_pk_mul_f32 v[90:91], v[150:151], v[90:91]
	v_lshl_add_u64 v[88:89], s[60:61], 0, v[88:89]
	v_cvt_pk_bf16_f32 v95, v90, v91
	v_lshl_add_u64 v[90:91], v[154:155], 1, v[88:89]
	v_cndmask_b32_e64 v88, v159, v100, s[0:1]
	s_and_b64 vcc, exec, s[6:7]
	v_lshlrev_b32_e32 v88, 7, v88
	global_store_dwordx4 v[90:91], v[92:95], off
	s_nop 1
	s_waitcnt vmcnt(9)
	v_mov_b64_e32 v[92:93], v[218:219]
	v_mov_b64_e32 v[94:95], v[220:221]
	v_mov_b64_e32 v[106:107], v[226:227]
	v_mov_b64_e32 v[108:109], v[228:229]
	v_pk_mul_f32 v[98:99], v[84:85], v[92:93]
	v_pk_mul_f32 v[102:103], v[84:85], v[106:107] op_sel:[1,0] op_sel_hi:[0,0]
	v_pk_mul_f32 v[106:107], v[86:87], v[106:107] op_sel:[1,1] op_sel_hi:[0,1]
	v_pk_mul_f32 v[110:111], v[80:81], v[108:109] op_sel:[1,0] op_sel_hi:[0,0]
	v_mov_b32_e32 v108, v95
	v_mul_f32_e32 v114, v83, v109
	v_mul_f32_e32 v116, v83, v95
	v_pk_fma_f32 v[84:85], v[84:85], v[92:93], v[102:103] op_sel_hi:[1,0,1]
	v_pk_fma_f32 v[118:119], v[86:87], v[92:93], v[106:107] op_sel:[0,1,0] neg_lo:[0,0,1] neg_hi:[0,0,1]
	v_pk_fma_f32 v[86:87], v[86:87], v[92:93], v[106:107] op_sel:[0,1,0]
	v_pk_fma_f32 v[92:93], v[80:81], v[94:95], v[110:111] op_sel_hi:[1,0,1] neg_lo:[0,0,1] neg_hi:[0,0,1]
	v_pk_fma_f32 v[80:81], v[80:81], v[94:95], v[110:111] op_sel_hi:[1,0,1]
	v_mov_b32_e32 v94, v109
	v_pk_fma_f32 v[106:107], v[82:83], v[108:109], v[114:115] op_sel_hi:[1,1,0] neg_lo:[0,0,1] neg_hi:[0,0,1]
	v_pk_fma_f32 v[94:95], v[82:83], v[94:95], v[116:117] op_sel_hi:[1,1,0]
	v_sub_f32_e32 v84, v98, v102
	v_mov_b32_e32 v86, v118
	v_mov_b32_e32 v80, v92
	v_mov_b32_e32 v82, v106
	v_mov_b32_e32 v83, v94
.Lrope_1277:
	v_pk_mul_f32 v[84:85], v[150:151], v[84:85]
	v_pk_mul_f32 v[80:81], v[150:151], v[80:81]
	v_pk_mul_f32 v[92:93], v[150:151], v[82:83]
	v_cvt_pk_bf16_f32 v82, v84, v85
	v_cvt_pk_bf16_f32 v84, v80, v81
	v_lshlrev_b64 v[80:81], 13, v[152:153]
	v_lshl_add_u64 v[80:81], s[60:61], 0, v[80:81]
	v_pk_mul_f32 v[86:87], v[150:151], v[86:87]
	v_lshl_add_u64 v[80:81], v[154:155], 1, v[80:81]
	v_cvt_pk_bf16_f32 v83, v86, v87
	v_add_co_u32_e32 v86, vcc, 0x120000, v80
	v_cvt_pk_bf16_f32 v85, v92, v93
	s_nop 0
	v_addc_co_u32_e32 v87, vcc, 0, v81, vcc
	global_store_dwordx4 v[86:87], v[82:85], off
	s_and_b64 vcc, exec, s[6:7]
	s_nop 0
	v_cndmask_b32_e64 v82, v160, v100, s[0:1]
	v_lshlrev_b32_e32 v82, 7, v82
	s_nop 1
	s_waitcnt vmcnt(8)
	v_mov_b64_e32 v[84:85], v[234:235]
	v_mov_b64_e32 v[86:87], v[236:237]
	v_mov_b64_e32 v[92:93], v[238:239]
	v_mov_b64_e32 v[94:95], v[240:241]
	v_pk_mul_f32 v[98:99], v[76:77], v[84:85]
	v_pk_mul_f32 v[102:103], v[76:77], v[92:93] op_sel:[1,0] op_sel_hi:[0,0]
	v_pk_mul_f32 v[92:93], v[78:79], v[92:93] op_sel:[1,1] op_sel_hi:[0,1]
	v_pk_mul_f32 v[106:107], v[72:73], v[94:95] op_sel:[1,0] op_sel_hi:[0,0]
	v_mov_b32_e32 v94, v87
	v_mul_f32_e32 v108, v75, v95
	v_mul_f32_e32 v110, v75, v87
	v_pk_fma_f32 v[76:77], v[76:77], v[84:85], v[102:103] op_sel_hi:[1,0,1]
	v_pk_fma_f32 v[114:115], v[78:79], v[84:85], v[92:93] op_sel:[0,1,0] neg_lo:[0,0,1] neg_hi:[0,0,1]
	v_pk_fma_f32 v[78:79], v[78:79], v[84:85], v[92:93] op_sel:[0,1,0]
	v_pk_fma_f32 v[84:85], v[72:73], v[86:87], v[106:107] op_sel_hi:[1,0,1] neg_lo:[0,0,1] neg_hi:[0,0,1]
	v_pk_fma_f32 v[72:73], v[72:73], v[86:87], v[106:107] op_sel_hi:[1,0,1]
	v_mov_b32_e32 v86, v95
	v_pk_fma_f32 v[92:93], v[74:75], v[94:95], v[108:109] op_sel_hi:[1,1,0] neg_lo:[0,0,1] neg_hi:[0,0,1]
	v_pk_fma_f32 v[86:87], v[74:75], v[86:87], v[110:111] op_sel_hi:[1,1,0]
	v_sub_f32_e32 v76, v98, v102
	v_mov_b32_e32 v78, v114
	v_mov_b32_e32 v72, v84
	v_mov_b32_e32 v74, v92
	v_mov_b32_e32 v75, v86
.Lrope_1279:
	v_pk_mul_f32 v[76:77], v[150:151], v[76:77]
	v_pk_mul_f32 v[78:79], v[150:151], v[78:79]
	v_pk_mul_f32 v[84:85], v[150:151], v[72:73]
	v_pk_mul_f32 v[86:87], v[150:151], v[74:75]
	v_cvt_pk_bf16_f32 v72, v76, v77
	v_add_co_u32_e32 v76, vcc, 0x140000, v80
	v_cvt_pk_bf16_f32 v73, v78, v79
	v_cvt_pk_bf16_f32 v74, v84, v85
	v_cvt_pk_bf16_f32 v75, v86, v87
	v_addc_co_u32_e32 v77, vcc, 0, v81, vcc
	global_store_dwordx4 v[76:77], v[72:75], off
	s_and_b64 vcc, exec, s[6:7]
	s_nop 0
	v_cndmask_b32_e64 v72, v161, v100, s[0:1]
	v_lshlrev_b32_e32 v72, 7, v72
	s_nop 1
	s_waitcnt vmcnt(7)
	v_mov_b64_e32 v[74:75], v[242:243]
	v_mov_b64_e32 v[76:77], v[244:245]
	v_mov_b64_e32 v[84:85], v[246:247]
	v_mov_b64_e32 v[86:87], v[248:249]
	v_pk_mul_f32 v[78:79], v[68:69], v[74:75]
	v_pk_mul_f32 v[92:93], v[68:69], v[84:85] op_sel:[1,0] op_sel_hi:[0,0]
	v_pk_mul_f32 v[84:85], v[70:71], v[84:85] op_sel:[1,1] op_sel_hi:[0,1]
	v_pk_mul_f32 v[94:95], v[64:65], v[86:87] op_sel:[1,0] op_sel_hi:[0,0]
	v_mov_b32_e32 v86, v77
	v_mul_f32_e32 v98, v67, v87
	v_mul_f32_e32 v100, v67, v77
	v_pk_fma_f32 v[68:69], v[68:69], v[74:75], v[92:93] op_sel_hi:[1,0,1]
	v_pk_fma_f32 v[102:103], v[70:71], v[74:75], v[84:85] op_sel:[0,1,0] neg_lo:[0,0,1] neg_hi:[0,0,1]
	v_pk_fma_f32 v[70:71], v[70:71], v[74:75], v[84:85] op_sel:[0,1,0]
	v_pk_fma_f32 v[74:75], v[64:65], v[76:77], v[94:95] op_sel_hi:[1,0,1] neg_lo:[0,0,1] neg_hi:[0,0,1]
	v_pk_fma_f32 v[64:65], v[64:65], v[76:77], v[94:95] op_sel_hi:[1,0,1]
	v_mov_b32_e32 v76, v87
	v_pk_fma_f32 v[84:85], v[66:67], v[86:87], v[98:99] op_sel_hi:[1,1,0] neg_lo:[0,0,1] neg_hi:[0,0,1]
	v_pk_fma_f32 v[76:77], v[66:67], v[76:77], v[100:101] op_sel_hi:[1,1,0]
	v_sub_f32_e32 v68, v78, v92
	v_mov_b32_e32 v70, v102
	v_mov_b32_e32 v64, v74
	v_mov_b32_e32 v66, v84
	v_mov_b32_e32 v67, v76
.Lrope_1281:
	v_pk_mul_f32 v[68:69], v[150:151], v[68:69]
	v_pk_mul_f32 v[64:65], v[150:151], v[64:65]
	v_pk_mul_f32 v[74:75], v[150:151], v[66:67]
	v_cvt_pk_bf16_f32 v66, v68, v69
	v_cvt_pk_bf16_f32 v68, v64, v65
	v_lshlrev_b64 v[64:65], 13, v[152:153]
	v_lshl_add_u64 v[64:65], s[60:61], 0, v[64:65]
	v_pk_mul_f32 v[70:71], v[150:151], v[70:71]
	v_lshl_add_u64 v[64:65], v[154:155], 1, v[64:65]
	v_cvt_pk_bf16_f32 v67, v70, v71
	v_add_co_u32_e32 v70, vcc, 0x160000, v64
	v_cvt_pk_bf16_f32 v69, v74, v75
	s_nop 0
	v_addc_co_u32_e32 v71, vcc, 0, v65, vcc
	s_and_b64 vcc, exec, s[6:7]
	global_store_dwordx4 v[70:71], v[66:69], off
	s_nop 1
	v_mov_b64_e32 v[66:67], v[178:179]
	v_mov_b64_e32 v[68:69], v[180:181]
	v_mov_b64_e32 v[74:75], v[182:183]
	v_mov_b64_e32 v[76:77], v[184:185]
	v_pk_mul_f32 v[70:71], v[60:61], v[66:67]
	v_pk_mul_f32 v[78:79], v[60:61], v[74:75] op_sel:[1,0] op_sel_hi:[0,0]
	v_pk_mul_f32 v[74:75], v[62:63], v[74:75] op_sel:[1,1] op_sel_hi:[0,1]
	v_pk_mul_f32 v[84:85], v[56:57], v[76:77] op_sel:[1,0] op_sel_hi:[0,0]
	v_mov_b32_e32 v76, v69
	v_mul_f32_e32 v86, v59, v77
	v_mul_f32_e32 v92, v59, v69
	v_pk_fma_f32 v[60:61], v[60:61], v[66:67], v[78:79] op_sel_hi:[1,0,1]
	v_pk_fma_f32 v[94:95], v[62:63], v[66:67], v[74:75] op_sel:[0,1,0] neg_lo:[0,0,1] neg_hi:[0,0,1]
	v_pk_fma_f32 v[62:63], v[62:63], v[66:67], v[74:75] op_sel:[0,1,0]
	v_pk_fma_f32 v[66:67], v[56:57], v[68:69], v[84:85] op_sel_hi:[1,0,1] neg_lo:[0,0,1] neg_hi:[0,0,1]
	v_pk_fma_f32 v[56:57], v[56:57], v[68:69], v[84:85] op_sel_hi:[1,0,1]
	v_mov_b32_e32 v68, v77
	v_pk_fma_f32 v[74:75], v[58:59], v[76:77], v[86:87] op_sel_hi:[1,1,0] neg_lo:[0,0,1] neg_hi:[0,0,1]
	v_pk_fma_f32 v[68:69], v[58:59], v[68:69], v[92:93] op_sel_hi:[1,1,0]
	v_sub_f32_e32 v60, v70, v78
	v_mov_b32_e32 v62, v94
	v_mov_b32_e32 v56, v66
	v_mov_b32_e32 v58, v74
	v_mov_b32_e32 v59, v68
.Lrope_1283:
	v_pk_mul_f32 v[60:61], v[150:151], v[60:61]
	v_pk_mul_f32 v[62:63], v[150:151], v[62:63]
	v_pk_mul_f32 v[66:67], v[150:151], v[56:57]
	v_pk_mul_f32 v[68:69], v[150:151], v[58:59]
	v_cvt_pk_bf16_f32 v56, v60, v61
	v_cvt_pk_bf16_f32 v57, v62, v63
	v_cvt_pk_bf16_f32 v58, v66, v67
	v_cvt_pk_bf16_f32 v59, v68, v69
	s_and_b64 vcc, exec, s[6:7]
	global_store_dwordx4 v[120:121], v[56:59], off offset:256
	s_nop 1
	v_mov_b64_e32 v[56:57], v[186:187]
	v_mov_b64_e32 v[58:59], v[188:189]
	v_mov_b64_e32 v[60:61], v[190:191]
	v_mov_b64_e32 v[62:63], v[192:193]
	v_pk_mul_f32 v[66:67], v[52:53], v[56:57]
	v_pk_mul_f32 v[68:69], v[52:53], v[60:61] op_sel:[1,0] op_sel_hi:[0,0]
	v_pk_mul_f32 v[60:61], v[54:55], v[60:61] op_sel:[1,1] op_sel_hi:[0,1]
	v_pk_mul_f32 v[70:71], v[48:49], v[62:63] op_sel:[1,0] op_sel_hi:[0,0]
	v_mov_b32_e32 v62, v59
	v_mul_f32_e32 v74, v51, v63
	v_mul_f32_e32 v76, v51, v59
	v_pk_fma_f32 v[52:53], v[52:53], v[56:57], v[68:69] op_sel_hi:[1,0,1]
	v_pk_fma_f32 v[78:79], v[54:55], v[56:57], v[60:61] op_sel:[0,1,0] neg_lo:[0,0,1] neg_hi:[0,0,1]
	v_pk_fma_f32 v[54:55], v[54:55], v[56:57], v[60:61] op_sel:[0,1,0]
	v_pk_fma_f32 v[56:57], v[48:49], v[58:59], v[70:71] op_sel_hi:[1,0,1] neg_lo:[0,0,1] neg_hi:[0,0,1]
	v_pk_fma_f32 v[48:49], v[48:49], v[58:59], v[70:71] op_sel_hi:[1,0,1]
	v_mov_b32_e32 v58, v63
	v_pk_fma_f32 v[60:61], v[50:51], v[62:63], v[74:75] op_sel_hi:[1,1,0] neg_lo:[0,0,1] neg_hi:[0,0,1]
	v_pk_fma_f32 v[58:59], v[50:51], v[58:59], v[76:77] op_sel_hi:[1,1,0]
	v_sub_f32_e32 v52, v66, v68
	v_mov_b32_e32 v54, v78
	v_mov_b32_e32 v48, v56
	v_mov_b32_e32 v50, v60
	v_mov_b32_e32 v51, v58
.Lrope_1285:
	v_pk_mul_f32 v[52:53], v[150:151], v[52:53]
	v_pk_mul_f32 v[54:55], v[150:151], v[54:55]
	v_pk_mul_f32 v[56:57], v[150:151], v[48:49]
	v_pk_mul_f32 v[58:59], v[150:151], v[50:51]
	v_cvt_pk_bf16_f32 v48, v52, v53
	v_cvt_pk_bf16_f32 v49, v54, v55
	v_cvt_pk_bf16_f32 v50, v56, v57
	v_cvt_pk_bf16_f32 v51, v58, v59
	s_and_b64 vcc, exec, s[6:7]
	global_store_dwordx4 v[112:113], v[48:51], off offset:256
	s_nop 1
	v_mov_b64_e32 v[48:49], v[194:195]
	v_mov_b64_e32 v[50:51], v[196:197]
	v_mov_b64_e32 v[52:53], v[198:199]
	v_mov_b64_e32 v[54:55], v[200:201]
	v_pk_mul_f32 v[56:57], v[44:45], v[48:49]
	v_pk_mul_f32 v[58:59], v[44:45], v[52:53] op_sel:[1,0] op_sel_hi:[0,0]
	v_pk_mul_f32 v[52:53], v[46:47], v[52:53] op_sel:[1,1] op_sel_hi:[0,1]
	v_pk_mul_f32 v[60:61], v[40:41], v[54:55] op_sel:[1,0] op_sel_hi:[0,0]
	v_mov_b32_e32 v54, v51
	v_mul_f32_e32 v62, v43, v55
	v_mul_f32_e32 v66, v43, v51
	v_pk_fma_f32 v[44:45], v[44:45], v[48:49], v[58:59] op_sel_hi:[1,0,1]
	v_pk_fma_f32 v[68:69], v[46:47], v[48:49], v[52:53] op_sel:[0,1,0] neg_lo:[0,0,1] neg_hi:[0,0,1]
	v_pk_fma_f32 v[46:47], v[46:47], v[48:49], v[52:53] op_sel:[0,1,0]
	v_pk_fma_f32 v[48:49], v[40:41], v[50:51], v[60:61] op_sel_hi:[1,0,1] neg_lo:[0,0,1] neg_hi:[0,0,1]
	v_pk_fma_f32 v[40:41], v[40:41], v[50:51], v[60:61] op_sel_hi:[1,0,1]
	v_mov_b32_e32 v50, v55
	v_pk_fma_f32 v[52:53], v[42:43], v[54:55], v[62:63] op_sel_hi:[1,1,0] neg_lo:[0,0,1] neg_hi:[0,0,1]
	v_pk_fma_f32 v[50:51], v[42:43], v[50:51], v[66:67] op_sel_hi:[1,1,0]
	v_sub_f32_e32 v44, v56, v58
	v_mov_b32_e32 v46, v68
	v_mov_b32_e32 v40, v48
	v_mov_b32_e32 v42, v52
	v_mov_b32_e32 v43, v50
.Lrope_1287:
	v_pk_mul_f32 v[44:45], v[150:151], v[44:45]
	v_pk_mul_f32 v[46:47], v[150:151], v[46:47]
	v_pk_mul_f32 v[48:49], v[150:151], v[40:41]
	v_pk_mul_f32 v[50:51], v[150:151], v[42:43]
	v_cvt_pk_bf16_f32 v40, v44, v45
	v_cvt_pk_bf16_f32 v41, v46, v47
	v_cvt_pk_bf16_f32 v42, v48, v49
	v_cvt_pk_bf16_f32 v43, v50, v51
	s_and_b64 vcc, exec, s[6:7]
	global_store_dwordx4 v[104:105], v[40:43], off offset:256
	s_nop 1
	v_mov_b64_e32 v[40:41], v[202:203]
	v_mov_b64_e32 v[42:43], v[204:205]
	v_mov_b64_e32 v[44:45], v[206:207]
	v_mov_b64_e32 v[46:47], v[208:209]
	v_pk_mul_f32 v[48:49], v[36:37], v[40:41]
	v_pk_mul_f32 v[50:51], v[36:37], v[44:45] op_sel:[1,0] op_sel_hi:[0,0]
	v_pk_mul_f32 v[44:45], v[38:39], v[44:45] op_sel:[1,1] op_sel_hi:[0,1]
	v_pk_mul_f32 v[52:53], v[32:33], v[46:47] op_sel:[1,0] op_sel_hi:[0,0]
	v_mov_b32_e32 v46, v43
	v_mul_f32_e32 v54, v35, v47
	v_mul_f32_e32 v56, v35, v43
	v_pk_fma_f32 v[36:37], v[36:37], v[40:41], v[50:51] op_sel_hi:[1,0,1]
	v_pk_fma_f32 v[58:59], v[38:39], v[40:41], v[44:45] op_sel:[0,1,0] neg_lo:[0,0,1] neg_hi:[0,0,1]
	v_pk_fma_f32 v[38:39], v[38:39], v[40:41], v[44:45] op_sel:[0,1,0]
	v_pk_fma_f32 v[40:41], v[32:33], v[42:43], v[52:53] op_sel_hi:[1,0,1] neg_lo:[0,0,1] neg_hi:[0,0,1]
	v_pk_fma_f32 v[32:33], v[32:33], v[42:43], v[52:53] op_sel_hi:[1,0,1]
	v_mov_b32_e32 v42, v47
	v_pk_fma_f32 v[44:45], v[34:35], v[46:47], v[54:55] op_sel_hi:[1,1,0] neg_lo:[0,0,1] neg_hi:[0,0,1]
	v_pk_fma_f32 v[42:43], v[34:35], v[42:43], v[56:57] op_sel_hi:[1,1,0]
	v_sub_f32_e32 v36, v48, v50
	v_mov_b32_e32 v38, v58
	v_mov_b32_e32 v32, v40
	v_mov_b32_e32 v34, v44
	v_mov_b32_e32 v35, v42
.Lrope_1289:
	v_pk_mul_f32 v[36:37], v[150:151], v[36:37]
	v_pk_mul_f32 v[38:39], v[150:151], v[38:39]
	v_pk_mul_f32 v[40:41], v[150:151], v[32:33]
	v_pk_mul_f32 v[42:43], v[150:151], v[34:35]
	v_cvt_pk_bf16_f32 v32, v36, v37
	v_cvt_pk_bf16_f32 v33, v38, v39
	v_cvt_pk_bf16_f32 v34, v40, v41
	v_cvt_pk_bf16_f32 v35, v42, v43
	s_and_b64 vcc, exec, s[6:7]
	global_store_dwordx4 v[96:97], v[32:35], off offset:256
	s_nop 1
	v_mov_b64_e32 v[32:33], v[210:211]
	v_mov_b64_e32 v[34:35], v[212:213]
	v_mov_b64_e32 v[36:37], v[214:215]
	v_mov_b64_e32 v[38:39], v[216:217]
	v_pk_mul_f32 v[40:41], v[28:29], v[32:33]
	v_pk_mul_f32 v[42:43], v[28:29], v[36:37] op_sel:[1,0] op_sel_hi:[0,0]
	v_pk_mul_f32 v[36:37], v[30:31], v[36:37] op_sel:[1,1] op_sel_hi:[0,1]
	v_pk_mul_f32 v[44:45], v[24:25], v[38:39] op_sel:[1,0] op_sel_hi:[0,0]
	v_mov_b32_e32 v38, v35
	v_mul_f32_e32 v46, v27, v39
	v_mul_f32_e32 v48, v27, v35
	v_pk_fma_f32 v[28:29], v[28:29], v[32:33], v[42:43] op_sel_hi:[1,0,1]
	v_pk_fma_f32 v[50:51], v[30:31], v[32:33], v[36:37] op_sel:[0,1,0] neg_lo:[0,0,1] neg_hi:[0,0,1]
	v_pk_fma_f32 v[30:31], v[30:31], v[32:33], v[36:37] op_sel:[0,1,0]
	v_pk_fma_f32 v[32:33], v[24:25], v[34:35], v[44:45] op_sel_hi:[1,0,1] neg_lo:[0,0,1] neg_hi:[0,0,1]
	v_pk_fma_f32 v[24:25], v[24:25], v[34:35], v[44:45] op_sel_hi:[1,0,1]
	v_mov_b32_e32 v34, v39
	v_pk_fma_f32 v[36:37], v[26:27], v[38:39], v[46:47] op_sel_hi:[1,1,0] neg_lo:[0,0,1] neg_hi:[0,0,1]
	v_pk_fma_f32 v[34:35], v[26:27], v[34:35], v[48:49] op_sel_hi:[1,1,0]
	v_sub_f32_e32 v28, v40, v42
	v_mov_b32_e32 v30, v50
	v_mov_b32_e32 v24, v32
	v_mov_b32_e32 v26, v36
	v_mov_b32_e32 v27, v34
.Lrope_1291:
	v_pk_mul_f32 v[28:29], v[150:151], v[28:29]
	v_pk_mul_f32 v[30:31], v[150:151], v[30:31]
	v_pk_mul_f32 v[32:33], v[150:151], v[24:25]
	v_pk_mul_f32 v[34:35], v[150:151], v[26:27]
	v_cvt_pk_bf16_f32 v24, v28, v29
	v_cvt_pk_bf16_f32 v25, v30, v31
	v_cvt_pk_bf16_f32 v26, v32, v33
	v_cvt_pk_bf16_f32 v27, v34, v35
	s_and_b64 vcc, exec, s[6:7]
	global_store_dwordx4 v[90:91], v[24:27], off offset:256
	s_nop 1
	v_mov_b64_e32 v[24:25], v[218:219]
	v_mov_b64_e32 v[26:27], v[220:221]
	v_mov_b64_e32 v[28:29], v[226:227]
	v_mov_b64_e32 v[30:31], v[228:229]
	v_pk_mul_f32 v[32:33], v[20:21], v[24:25]
	v_pk_mul_f32 v[34:35], v[20:21], v[28:29] op_sel:[1,0] op_sel_hi:[0,0]
	v_pk_mul_f32 v[28:29], v[22:23], v[28:29] op_sel:[1,1] op_sel_hi:[0,1]
	v_pk_mul_f32 v[36:37], v[16:17], v[30:31] op_sel:[1,0] op_sel_hi:[0,0]
	v_mov_b32_e32 v30, v27
	v_mul_f32_e32 v38, v19, v31
	v_mul_f32_e32 v40, v19, v27
	v_pk_fma_f32 v[20:21], v[20:21], v[24:25], v[34:35] op_sel_hi:[1,0,1]
	v_pk_fma_f32 v[42:43], v[22:23], v[24:25], v[28:29] op_sel:[0,1,0] neg_lo:[0,0,1] neg_hi:[0,0,1]
	v_pk_fma_f32 v[22:23], v[22:23], v[24:25], v[28:29] op_sel:[0,1,0]
	v_pk_fma_f32 v[24:25], v[16:17], v[26:27], v[36:37] op_sel_hi:[1,0,1] neg_lo:[0,0,1] neg_hi:[0,0,1]
	v_pk_fma_f32 v[16:17], v[16:17], v[26:27], v[36:37] op_sel_hi:[1,0,1]
	v_mov_b32_e32 v26, v31
	v_pk_fma_f32 v[28:29], v[18:19], v[30:31], v[38:39] op_sel_hi:[1,1,0] neg_lo:[0,0,1] neg_hi:[0,0,1]
	v_pk_fma_f32 v[26:27], v[18:19], v[26:27], v[40:41] op_sel_hi:[1,1,0]
	v_sub_f32_e32 v20, v32, v34
	v_mov_b32_e32 v22, v42
	v_mov_b32_e32 v16, v24
	v_mov_b32_e32 v18, v28
	v_mov_b32_e32 v19, v26
.Lrope_1293:
	v_pk_mul_f32 v[20:21], v[150:151], v[20:21]
	v_pk_mul_f32 v[22:23], v[150:151], v[22:23]
	v_pk_mul_f32 v[26:27], v[150:151], v[16:17]
	v_pk_mul_f32 v[28:29], v[150:151], v[18:19]
	v_lshl_add_u64 v[24:25], v[80:81], 0, s[38:39]
	v_cvt_pk_bf16_f32 v16, v20, v21
	v_cvt_pk_bf16_f32 v17, v22, v23
	v_cvt_pk_bf16_f32 v18, v26, v27
	v_cvt_pk_bf16_f32 v19, v28, v29
	s_and_b64 vcc, exec, s[6:7]
	global_store_dwordx4 v[24:25], v[16:19], off offset:256
	s_nop 1
	v_mov_b64_e32 v[16:17], v[234:235]
	v_mov_b64_e32 v[18:19], v[236:237]
	v_mov_b64_e32 v[20:21], v[238:239]
	v_mov_b64_e32 v[22:23], v[240:241]
	v_pk_mul_f32 v[24:25], v[12:13], v[16:17]
	v_pk_mul_f32 v[26:27], v[12:13], v[20:21] op_sel:[1,0] op_sel_hi:[0,0]
	v_pk_mul_f32 v[20:21], v[14:15], v[20:21] op_sel:[1,1] op_sel_hi:[0,1]
	v_pk_mul_f32 v[28:29], v[8:9], v[22:23] op_sel:[1,0] op_sel_hi:[0,0]
	v_mov_b32_e32 v22, v19
	v_mul_f32_e32 v30, v11, v23
	v_mul_f32_e32 v32, v11, v19
	v_pk_fma_f32 v[12:13], v[12:13], v[16:17], v[26:27] op_sel_hi:[1,0,1]
	v_pk_fma_f32 v[34:35], v[14:15], v[16:17], v[20:21] op_sel:[0,1,0] neg_lo:[0,0,1] neg_hi:[0,0,1]
	v_pk_fma_f32 v[14:15], v[14:15], v[16:17], v[20:21] op_sel:[0,1,0]
	v_pk_fma_f32 v[16:17], v[8:9], v[18:19], v[28:29] op_sel_hi:[1,0,1] neg_lo:[0,0,1] neg_hi:[0,0,1]
	v_pk_fma_f32 v[8:9], v[8:9], v[18:19], v[28:29] op_sel_hi:[1,0,1]
	v_mov_b32_e32 v18, v23
	v_pk_fma_f32 v[20:21], v[10:11], v[22:23], v[30:31] op_sel_hi:[1,1,0] neg_lo:[0,0,1] neg_hi:[0,0,1]
	v_pk_fma_f32 v[18:19], v[10:11], v[18:19], v[32:33] op_sel_hi:[1,1,0]
	v_sub_f32_e32 v12, v24, v26
	v_mov_b32_e32 v14, v34
	v_mov_b32_e32 v8, v16
	v_mov_b32_e32 v10, v20
	v_mov_b32_e32 v11, v18
.Lrope_1295:
	v_pk_mul_f32 v[12:13], v[150:151], v[12:13]
	v_pk_mul_f32 v[14:15], v[150:151], v[14:15]
	v_pk_mul_f32 v[18:19], v[150:151], v[8:9]
	v_pk_mul_f32 v[20:21], v[150:151], v[10:11]
	v_lshl_add_u64 v[16:17], v[80:81], 0, s[40:41]
	v_cvt_pk_bf16_f32 v8, v12, v13
	v_cvt_pk_bf16_f32 v9, v14, v15
	v_cvt_pk_bf16_f32 v10, v18, v19
	v_cvt_pk_bf16_f32 v11, v20, v21
	s_and_b64 vcc, exec, s[6:7]
	global_store_dwordx4 v[16:17], v[8:11], off offset:256
	s_nop 1
	v_mov_b64_e32 v[8:9], v[242:243]
	v_mov_b64_e32 v[10:11], v[244:245]
	v_mov_b64_e32 v[12:13], v[246:247]
	v_mov_b64_e32 v[14:15], v[248:249]
	v_pk_mul_f32 v[16:17], v[4:5], v[8:9]
	v_pk_mul_f32 v[18:19], v[4:5], v[12:13] op_sel:[1,0] op_sel_hi:[0,0]
	v_pk_mul_f32 v[12:13], v[6:7], v[12:13] op_sel:[1,1] op_sel_hi:[0,1]
	v_pk_mul_f32 v[20:21], v[0:1], v[14:15] op_sel:[1,0] op_sel_hi:[0,0]
	v_mov_b32_e32 v14, v11
	v_mul_f32_e32 v22, v3, v15
	v_mul_f32_e32 v24, v3, v11
	v_pk_fma_f32 v[4:5], v[4:5], v[8:9], v[18:19] op_sel_hi:[1,0,1]
	v_pk_fma_f32 v[26:27], v[6:7], v[8:9], v[12:13] op_sel:[0,1,0] neg_lo:[0,0,1] neg_hi:[0,0,1]
	v_pk_fma_f32 v[6:7], v[6:7], v[8:9], v[12:13] op_sel:[0,1,0]
	v_pk_fma_f32 v[8:9], v[0:1], v[10:11], v[20:21] op_sel_hi:[1,0,1] neg_lo:[0,0,1] neg_hi:[0,0,1]
	v_pk_fma_f32 v[0:1], v[0:1], v[10:11], v[20:21] op_sel_hi:[1,0,1]
	v_mov_b32_e32 v10, v15
	v_pk_fma_f32 v[12:13], v[2:3], v[14:15], v[22:23] op_sel_hi:[1,1,0] neg_lo:[0,0,1] neg_hi:[0,0,1]
	v_pk_fma_f32 v[10:11], v[2:3], v[10:11], v[24:25] op_sel_hi:[1,1,0]
	v_sub_f32_e32 v4, v16, v18
	v_mov_b32_e32 v6, v26
	v_mov_b32_e32 v0, v8
	v_mov_b32_e32 v2, v12
	v_mov_b32_e32 v3, v10
	s_branch .LBB0_1260
